# combined: head-major Q/K + retention chunk-permuted LDS rows + pipelined LDS reads + early next-chunk loads + hand-pipelined P0 gW/bW loop
# baseline (speedup 1.0000x reference)
.LBB0_438:
	s_waitcnt vmcnt(2)
	ds_write_b128 v176, v[2:5]
	ds_write_b128 v176, v[6:9] offset:33792
	ds_write_b128 v177, v[10:13]
	ds_write_b128 v177, v[14:17] offset:33792
	ds_write_b128 v178, v[18:21]
	ds_write_b128 v178, v[22:25] offset:33792
	ds_write_b128 v179, v[30:33]
	ds_write_b128 v179, v[34:37] offset:33792
	ds_write_b128 v180, v[26:29]
	v_lshlrev_b32_e32 v2, 16, v26
	v_and_b32_e32 v3, 0xffff0000, v26
	v_lshlrev_b32_e32 v4, 16, v27
	v_and_b32_e32 v5, 0xffff0000, v27
	v_pk_mul_f32 v[2:3], v[124:125], v[2:3]
	v_pk_mul_f32 v[4:5], v[124:125], v[4:5]
	v_cvt_pk_bf16_f32 v2, v2, v3
	v_cvt_pk_bf16_f32 v3, v4, v5
	v_lshlrev_b32_e32 v4, 16, v28
	v_and_b32_e32 v5, 0xffff0000, v28
	v_lshlrev_b32_e32 v6, 16, v29
	v_and_b32_e32 v7, 0xffff0000, v29
	v_pk_mul_f32 v[4:5], v[124:125], v[4:5]
	v_pk_mul_f32 v[6:7], v[124:125], v[6:7]
	v_cvt_pk_bf16_f32 v4, v4, v5
	v_cvt_pk_bf16_f32 v5, v6, v7
	v_lshl_add_u64 v[6:7], s[78:79], 0, v[122:123]
	ds_write_b128 v181, v[2:5]
	v_add_co_u32_e64 v2, s[36:37], s27, v6
	v_lshl_add_u64 v[14:15], s[78:79], 0, v[120:121]
	s_nop 0
	v_addc_co_u32_e64 v3, s[36:37], 0, v7, s[36:37]
	v_add_co_u32_e64 v6, s[36:37], s28, v6
	v_lshl_add_u64 v[22:23], s[78:79], 0, v[118:119]
	s_nop 0
	v_addc_co_u32_e64 v7, s[36:37], 0, v7, s[36:37]
	v_add_co_u32_e64 v10, s[36:37], s27, v14
	v_lshl_add_u64 v[26:27], s[78:79], 0, v[116:117]
	s_nop 0
	v_addc_co_u32_e64 v11, s[36:37], 0, v15, s[36:37]
	v_add_co_u32_e64 v14, s[36:37], s28, v14
	s_nop 0
	v_addc_co_u32_e64 v15, s[36:37], 0, v15, s[36:37]
	v_add_co_u32_e64 v18, s[36:37], s27, v22
	s_nop 0
	v_addc_co_u32_e64 v19, s[36:37], 0, v23, s[36:37]
	v_add_co_u32_e64 v22, s[36:37], s28, v22
	s_nop 1
	v_addc_co_u32_e64 v23, s[36:37], 0, v23, s[36:37]
	v_add_co_u32_e64 v28, s[36:37], s27, v26
	global_load_dwordx4 v[2:5], v[2:3], off
	s_nop 0
	v_addc_co_u32_e64 v29, s[36:37], 0, v27, s[36:37]
	v_add_co_u32_e64 v26, s[36:37], s28, v26
	global_load_dwordx4 v[30:33], v[28:29], off
	s_nop 0
	v_addc_co_u32_e64 v27, s[36:37], 0, v27, s[36:37]
	global_load_dwordx4 v[34:37], v[26:27], off
	v_lshl_add_u64 v[26:27], s[78:79], 0, v[114:115]
	global_load_dwordx4 v[6:9], v[6:7], off
	v_add_u32_e32 v205, v131, v127
	global_load_dwordx4 v[10:13], v[10:11], off
	s_mov_b32 s36, 0x59a00000
	global_load_dwordx4 v[14:17], v[14:15], off
	v_mov_b32_e32 v105, v104
	global_load_dwordx4 v[18:21], v[18:19], off
	v_pk_mul_f32 v[68:69], v[104:105], v[68:69]
	global_load_dwordx4 v[22:25], v[22:23], off
	v_pk_mul_f32 v[66:67], v[106:107], v[66:67]
	global_load_dwordx4 v[26:29], v[26:27], off
	s_waitcnt lgkmcnt(0)
	s_barrier
	ds_read_b128 v[70:73], v182
	ds_read_b128 v[74:77], v183 offset:33792
	ds_read_b128 v[188:191], v183 offset:42240
	ds_read_b128 v[210:213], v182 offset:16
	ds_read_b128 v[214:217], v183 offset:33808
	ds_read_b128 v[218:221], v183 offset:42256
	s_waitcnt lgkmcnt(4)
	v_mfma_f32_16x16x32_bf16 v[74:77], v[70:73], v[74:77], 0
	v_mul_f32_e64 v64, v104, v64
	v_mul_f32_e64 v65, v105, v65
	v_pk_mul_f32 v[62:63], v[106:107], v[62:63]
	v_pk_mul_f32 v[60:61], v[104:105], v[60:61]
	s_waitcnt lgkmcnt(3)
	v_mfma_f32_16x16x32_bf16 v[70:73], v[70:73], v[188:191], 0
	ds_read_b128 v[188:191], v182 offset:32
	ds_read_b128 v[192:195], v183 offset:33824
	ds_read_b128 v[206:209], v183 offset:42272
	v_pk_mul_f32 v[58:59], v[106:107], v[58:59]
	v_pk_mul_f32 v[48:49], v[104:105], v[48:49]
	s_waitcnt lgkmcnt(4)
	v_mfma_f32_16x16x32_bf16 v[74:77], v[210:213], v[214:217], v[74:77]
	v_mul_f32_e64 v46, v106, v46
	v_mul_f32_e64 v47, v107, v47
	v_pk_mul_f32 v[44:45], v[104:105], v[44:45]
	v_pk_mul_f32 v[42:43], v[106:107], v[42:43]
	s_waitcnt lgkmcnt(3)
	v_mfma_f32_16x16x32_bf16 v[70:73], v[210:213], v[218:221], v[70:73]
	ds_read_b128 v[210:213], v182 offset:48
	ds_read_b128 v[214:217], v183 offset:33840
	ds_read_b128 v[218:221], v183 offset:42288
	v_pk_mul_f32 v[40:41], v[104:105], v[40:41]
	v_pk_mul_f32 v[38:39], v[106:107], v[38:39]
	s_waitcnt lgkmcnt(4)
	v_mfma_f32_16x16x32_bf16 v[74:77], v[188:191], v[192:195], v[74:77]
	s_add_i32 s39, s39, -1
	v_lshl_add_u64 v[114:115], v[114:115], 0, s[34:35]
	v_lshl_add_u64 v[116:117], v[116:117], 0, s[86:87]
	s_waitcnt lgkmcnt(3)
	v_mfma_f32_16x16x32_bf16 v[70:73], v[188:191], v[206:209], v[70:73]
	ds_read_b128 v[188:191], v182 offset:64
	ds_read_b128 v[192:195], v183 offset:33856
	ds_read_b128 v[206:209], v183 offset:42304
	v_lshl_add_u64 v[118:119], v[118:119], 0, s[86:87]
	v_lshl_add_u64 v[120:121], v[120:121], 0, s[86:87]
	s_waitcnt lgkmcnt(4)
	v_mfma_f32_16x16x32_bf16 v[74:77], v[210:213], v[214:217], v[74:77]
	v_lshl_add_u64 v[122:123], v[122:123], 0, s[86:87]
	s_cmp_lg_u32 s39, 0
	s_waitcnt lgkmcnt(3)
	v_mfma_f32_16x16x32_bf16 v[70:73], v[210:213], v[218:221], v[70:73]
	ds_read_b128 v[210:213], v182 offset:80
	ds_read_b128 v[214:217], v183 offset:33872
	ds_read_b128 v[218:221], v183 offset:42320
	s_waitcnt lgkmcnt(4)
	v_mfma_f32_16x16x32_bf16 v[74:77], v[188:191], v[192:195], v[74:77]
	s_waitcnt lgkmcnt(3)
	v_mfma_f32_16x16x32_bf16 v[70:73], v[188:191], v[206:209], v[70:73]
	ds_read_b128 v[188:191], v182 offset:96
	ds_read_b128 v[192:195], v183 offset:33888
	ds_read_b128 v[206:209], v183 offset:42336
	s_waitcnt lgkmcnt(4)
	v_mfma_f32_16x16x32_bf16 v[74:77], v[210:213], v[214:217], v[74:77]
	s_waitcnt lgkmcnt(3)
	v_mfma_f32_16x16x32_bf16 v[70:73], v[210:213], v[218:221], v[70:73]
	ds_read_b128 v[210:213], v182 offset:112
	ds_read_b128 v[214:217], v183 offset:33904
	ds_read_b128 v[218:221], v183 offset:42352
	s_waitcnt lgkmcnt(4)
	v_mfma_f32_16x16x32_bf16 v[74:77], v[188:191], v[192:195], v[74:77]
	s_waitcnt lgkmcnt(3)
	v_mfma_f32_16x16x32_bf16 v[70:73], v[188:191], v[206:209], v[70:73]
	s_waitcnt lgkmcnt(1)
	v_mfma_f32_16x16x32_bf16 v[74:77], v[210:213], v[214:217], v[74:77]
	s_waitcnt lgkmcnt(0)
	v_mfma_f32_16x16x32_bf16 v[70:73], v[210:213], v[218:221], v[70:73]
	s_nop 5
	v_mul_f32_e32 v1, v103, v74
	v_cvt_pk_bf16_f32 v1, v1, s0
	v_add_u32_e32 v74, v131, v126
	ds_write_b16 v74, v1
	v_add_u32_e32 v206, v134, v127
	v_mul_f32_e32 v1, v198, v70
	v_cvt_pk_bf16_f32 v1, v1, s0
	ds_write_b16 v205, v1
	v_mul_f32_e32 v1, v199, v75
	v_cvt_pk_bf16_f32 v1, v1, s0
	v_add_u32_e32 v75, v134, v126
	ds_write_b16 v75, v1
	v_mul_f32_e32 v1, v200, v71
	v_cvt_pk_bf16_f32 v1, v1, s0
	ds_write_b16 v206, v1
	v_mul_f32_e32 v1, v201, v76
	v_cvt_pk_bf16_f32 v1, v1, s0
	v_add_u32_e32 v76, v137, v126
	ds_write_b16 v76, v1
	v_mul_f32_e32 v1, v202, v72
	v_cvt_pk_bf16_f32 v1, v1, s0
	v_add_u32_e32 v207, v137, v127
	ds_write_b16 v207, v1
	v_mul_f32_e32 v1, v203, v77
	v_cvt_pk_bf16_f32 v1, v1, s0
	v_add_u32_e32 v77, v140, v126
	ds_write_b16 v77, v1
	v_mul_f32_e32 v1, v204, v73
	v_cvt_pk_bf16_f32 v1, v1, s0
	v_add_u32_e32 v208, v140, v127
	ds_write_b16 v208, v1
	s_waitcnt lgkmcnt(0)
	s_barrier
	ds_read_b128 v[70:73], v182
	ds_read_b128 v[188:191], v184
	ds_read_b128 v[192:195], v184 offset:8448
	ds_read_b128 v[222:225], v182 offset:16
	ds_read_b128 v[218:221], v184 offset:16
	ds_read_b128 v[242:245], v184 offset:8464
	s_waitcnt lgkmcnt(4)
	v_mfma_f32_16x16x32_bf16 v[188:191], v[188:191], v[70:73], 0
	s_waitcnt lgkmcnt(3)
	v_mfma_f32_16x16x32_bf16 v[70:73], v[192:195], v[70:73], 0
	ds_read_b128 v[192:195], v182 offset:32
	ds_read_b128 v[210:213], v184 offset:32
	ds_read_b128 v[214:217], v184 offset:8480
	s_waitcnt lgkmcnt(4)
	v_mfma_f32_16x16x32_bf16 v[188:191], v[218:221], v[222:225], v[188:191]
	s_waitcnt lgkmcnt(3)
	v_mfma_f32_16x16x32_bf16 v[70:73], v[242:245], v[222:225], v[70:73]
	ds_read_b128 v[222:225], v182 offset:48
	ds_read_b128 v[218:221], v184 offset:48
	ds_read_b128 v[242:245], v184 offset:8496
	s_waitcnt lgkmcnt(4)
	v_mfma_f32_16x16x32_bf16 v[188:191], v[210:213], v[192:195], v[188:191]
	s_waitcnt lgkmcnt(3)
	v_mfma_f32_16x16x32_bf16 v[70:73], v[214:217], v[192:195], v[70:73]
	ds_read_b128 v[192:195], v182 offset:64
	ds_read_b128 v[210:213], v184 offset:64
	ds_read_b128 v[214:217], v184 offset:8512
	s_waitcnt lgkmcnt(4)
	v_mfma_f32_16x16x32_bf16 v[188:191], v[218:221], v[222:225], v[188:191]
	s_waitcnt lgkmcnt(3)
	v_mfma_f32_16x16x32_bf16 v[70:73], v[242:245], v[222:225], v[70:73]
	ds_read_b128 v[222:225], v182 offset:80
	ds_read_b128 v[218:221], v184 offset:80
	ds_read_b128 v[242:245], v184 offset:8528
	s_waitcnt lgkmcnt(4)
	v_mfma_f32_16x16x32_bf16 v[188:191], v[210:213], v[192:195], v[188:191]
	s_waitcnt lgkmcnt(3)
	v_mfma_f32_16x16x32_bf16 v[70:73], v[214:217], v[192:195], v[70:73]
	ds_read_b128 v[192:195], v182 offset:96
	ds_read_b128 v[210:213], v184 offset:96
	ds_read_b128 v[214:217], v184 offset:8544
	s_waitcnt lgkmcnt(4)
	v_mfma_f32_16x16x32_bf16 v[188:191], v[218:221], v[222:225], v[188:191]
	s_waitcnt lgkmcnt(3)
	v_mfma_f32_16x16x32_bf16 v[70:73], v[242:245], v[222:225], v[70:73]
	ds_read_b128 v[222:225], v182 offset:112
	ds_read_b128 v[218:221], v184 offset:112
	ds_read_b128 v[242:245], v184 offset:8560
	s_waitcnt lgkmcnt(4)
	v_mfma_f32_16x16x32_bf16 v[188:191], v[210:213], v[192:195], v[188:191]
	s_waitcnt lgkmcnt(3)
	v_mfma_f32_16x16x32_bf16 v[70:73], v[214:217], v[192:195], v[70:73]
	s_waitcnt lgkmcnt(1)
	v_mfma_f32_16x16x32_bf16 v[188:191], v[218:221], v[222:225], v[188:191]
	s_waitcnt lgkmcnt(0)
	v_mfma_f32_16x16x32_bf16 v[70:73], v[242:245], v[222:225], v[70:73]
	ds_read_b128 v[192:195], v185
	s_nop 4
	v_pk_mul_f32 v[190:191], v[110:111], v[190:191]
	v_pk_mul_f32 v[188:189], v[108:109], v[188:189]
	ds_read_b64_tr_b16 v[214:215], v141
	ds_read_b64_tr_b16 v[216:217], v142
	ds_read_b64_tr_b16 v[210:211], v143
	ds_read_b64_tr_b16 v[212:213], v144
	s_waitcnt lgkmcnt(0)
	s_waitcnt lgkmcnt(0)
	s_nop 0
	v_mfma_f32_16x16x32_bf16 v[188:191], v[214:217], v[192:195], v[188:191]
	v_mul_f32_e64 v72, v110, v72
	v_mul_f32_e64 v73, v111, v73
	v_pk_mul_f32 v[70:71], v[108:109], v[70:71]
	s_nop 1
	v_mfma_f32_16x16x32_bf16 v[70:73], v[210:213], v[192:195], v[70:73]
	ds_read_b128 v[192:195], v185 offset:64
	ds_read_b64_tr_b16 v[214:215], v145
	ds_read_b64_tr_b16 v[216:217], v146
	ds_read_b64_tr_b16 v[210:211], v147
	ds_read_b64_tr_b16 v[212:213], v148
	s_waitcnt lgkmcnt(0)
	s_waitcnt lgkmcnt(0)
	v_mfma_f32_16x16x32_bf16 v[188:191], v[214:217], v[192:195], v[188:191]
	v_mfma_f32_16x16x32_bf16 v[192:195], v[210:213], v[192:195], v[70:73]
	s_nop 6
	v_cvt_pk_bf16_f32 v70, v188, v189
	v_lshl_add_u64 v[188:189], s[78:79], 0, v[112:113]
	v_add_co_u32_e64 v188, s[36:37], s36, v188
	v_cvt_pk_bf16_f32 v71, v190, v191
	s_nop 0
	v_addc_co_u32_e64 v189, s[36:37], 0, v189, s[36:37]
	v_cvt_pk_bf16_f32 v72, v192, v193
	v_cvt_pk_bf16_f32 v73, v194, v195
	global_store_dwordx2 v[188:189], v[70:71], off
	global_store_dwordx2 v[188:189], v[72:73], off offset:32
	v_pk_mul_f32 v[72:73], v[104:105], v[52:53]
	v_pk_mul_f32 v[70:71], v[106:107], v[50:51]
	v_pk_mul_f32 v[52:53], v[104:105], v[56:57]
	v_pk_mul_f32 v[50:51], v[106:107], v[54:55]
	ds_read_b64_tr_b16 v[188:189], v149
	ds_read_b64_tr_b16 v[190:191], v151
	ds_read_b64_tr_b16 v[54:55], v152
	ds_read_b64_tr_b16 v[56:57], v153
	ds_read_b64_tr_b16 v[210:211], v150
	ds_read_b64_tr_b16 v[212:213], v154
	ds_read_b64_tr_b16 v[192:193], v155
	ds_read_b64_tr_b16 v[194:195], v156
	ds_read_b64_tr_b16 v[218:219], v157
	ds_read_b64_tr_b16 v[220:221], v158
	ds_read_b64_tr_b16 v[214:215], v159
	ds_read_b64_tr_b16 v[216:217], v160
	s_waitcnt lgkmcnt(0)
	v_lshl_add_u64 v[112:113], v[112:113], 0, s[34:35]
	v_mfma_f32_16x16x32_bf16 v[66:69], v[188:191], v[210:213], v[66:69]
	v_mfma_f32_16x16x32_bf16 v[62:65], v[188:191], v[192:195], v[62:65]
	v_mfma_f32_16x16x32_bf16 v[58:61], v[188:191], v[218:221], v[58:61]
	v_mfma_f32_16x16x32_bf16 v[70:73], v[188:191], v[214:217], v[70:73]
	v_mfma_f32_16x16x32_bf16 v[188:191], v[54:57], v[210:213], v[50:53]
	v_mfma_f32_16x16x32_bf16 v[46:49], v[54:57], v[192:195], v[46:49]
	ds_read_b64_tr_b16 v[50:51], v161
	ds_read_b64_tr_b16 v[52:53], v163
	ds_read_b64_tr_b16 v[192:193], v164
	ds_read_b64_tr_b16 v[194:195], v165
	s_waitcnt lgkmcnt(0)
	v_mfma_f32_16x16x32_bf16 v[42:45], v[54:57], v[218:221], v[42:45]
	v_mfma_f32_16x16x32_bf16 v[38:41], v[54:57], v[214:217], v[38:41]
	ds_read_b64_tr_b16 v[54:55], v162
	ds_read_b64_tr_b16 v[56:57], v166
	ds_read_b64_tr_b16 v[210:211], v167
	ds_read_b64_tr_b16 v[212:213], v168
	s_waitcnt lgkmcnt(0)
	ds_read_b64_tr_b16 v[218:219], v169
	ds_read_b64_tr_b16 v[220:221], v170
	ds_read_b64_tr_b16 v[214:215], v171
	ds_read_b64_tr_b16 v[216:217], v172
	s_waitcnt lgkmcnt(0)
	s_nop 0
	v_mfma_f32_16x16x32_bf16 v[66:69], v[50:53], v[54:57], v[66:69]
	s_barrier
	v_mfma_f32_16x16x32_bf16 v[62:65], v[50:53], v[210:213], v[62:65]
	v_mfma_f32_16x16x32_bf16 v[58:61], v[50:53], v[218:221], v[58:61]
	v_mfma_f32_16x16x32_bf16 v[50:53], v[50:53], v[214:217], v[70:73]
	v_mfma_f32_16x16x32_bf16 v[54:57], v[192:195], v[54:57], v[188:191]
	s_nop 2
	v_cvt_pk_bf16_f32 v70, v66, v67
	v_cvt_pk_bf16_f32 v71, v68, v69
	ds_write_b64 v196, v[70:71]
	v_mfma_f32_16x16x32_bf16 v[46:49], v[192:195], v[210:213], v[46:49]
	v_cvt_pk_bf16_f32 v70, v62, v63
	v_cvt_pk_bf16_f32 v71, v64, v65
	ds_write_b64 v196, v[70:71] offset:8448
	v_mfma_f32_16x16x32_bf16 v[42:45], v[192:195], v[218:221], v[42:45]
	v_cvt_pk_bf16_f32 v70, v58, v59
	v_cvt_pk_bf16_f32 v71, v60, v61
	ds_write_b64 v196, v[70:71] offset:16896
	v_mfma_f32_16x16x32_bf16 v[38:41], v[192:195], v[214:217], v[38:41]
	v_cvt_pk_bf16_f32 v70, v50, v51
	v_cvt_pk_bf16_f32 v71, v52, v53
	ds_write_b64 v196, v[70:71] offset:25344
	v_cvt_pk_bf16_f32 v70, v54, v55
	v_cvt_pk_bf16_f32 v71, v56, v57
	ds_write_b64 v197, v[70:71]
	v_cvt_pk_bf16_f32 v70, v46, v47
	v_cvt_pk_bf16_f32 v71, v48, v49
	ds_write_b64 v197, v[70:71] offset:8448
	v_cvt_pk_bf16_f32 v70, v42, v43
	v_cvt_pk_bf16_f32 v71, v44, v45
	ds_write_b64 v197, v[70:71] offset:16896
	v_cvt_pk_bf16_f32 v70, v38, v39
	v_cvt_pk_bf16_f32 v71, v40, v41
	ds_write_b64 v197, v[70:71] offset:25344
	s_cbranch_scc1 .LBB0_438
	s_waitcnt vmcnt(10)
	ds_write_b128 v176, v[2:5]
	s_waitcnt vmcnt(7)
	ds_write_b128 v176, v[6:9] offset:33792
	s_waitcnt vmcnt(6)
	ds_write_b128 v177, v[10:13]
	s_waitcnt vmcnt(5)
	ds_write_b128 v177, v[14:17] offset:33792
	s_waitcnt vmcnt(4)
	ds_write_b128 v178, v[18:21]
	s_waitcnt vmcnt(3)
	ds_write_b128 v178, v[22:25] offset:33792
	ds_write_b128 v179, v[30:33]
	ds_write_b128 v179, v[34:37] offset:33792
	s_waitcnt vmcnt(2)
	ds_write_b128 v180, v[26:29]
	v_lshlrev_b32_e32 v2, 16, v26
	v_and_b32_e32 v3, 0xffff0000, v26
	v_lshlrev_b32_e32 v4, 16, v27
	v_and_b32_e32 v5, 0xffff0000, v27
	v_pk_mul_f32 v[2:3], v[124:125], v[2:3]
	v_pk_mul_f32 v[4:5], v[124:125], v[4:5]
	v_cvt_pk_bf16_f32 v2, v2, v3
	v_cvt_pk_bf16_f32 v3, v4, v5
	v_lshlrev_b32_e32 v4, 16, v28
	v_and_b32_e32 v5, 0xffff0000, v28
	v_lshlrev_b32_e32 v6, 16, v29
	v_and_b32_e32 v7, 0xffff0000, v29
	v_pk_mul_f32 v[4:5], v[124:125], v[4:5]
	v_pk_mul_f32 v[6:7], v[124:125], v[6:7]
	v_cvt_pk_bf16_f32 v4, v4, v5
	v_cvt_pk_bf16_f32 v5, v6, v7
	ds_write_b128 v181, v[2:5]
	s_waitcnt lgkmcnt(0)
	s_barrier
	ds_read_b128 v[2:5], v182
	ds_read_b128 v[6:9], v183 offset:33792
	ds_read_b128 v[10:13], v182 offset:16
	ds_read_b128 v[14:17], v183 offset:33808
	s_waitcnt lgkmcnt(2)
	v_mfma_f32_16x16x32_bf16 v[6:9], v[2:5], v[6:9], 0
	ds_read_b128 v[18:21], v183 offset:42240
	ds_read_b128 v[22:25], v183 offset:42256
	s_lshl_b32 s15, s15, 1
	s_add_u32 s15, s7, s15
	s_waitcnt lgkmcnt(2)
	v_mfma_f32_16x16x32_bf16 v[6:9], v[10:13], v[14:17], v[6:9]
	ds_read_b128 v[14:17], v182 offset:32
	s_addc_u32 s39, s10, 0
	s_lshl_b64 s[36:37], s[40:41], 1
	s_waitcnt lgkmcnt(2)
	v_mfma_f32_16x16x32_bf16 v[2:5], v[2:5], v[18:21], 0
	s_add_u32 s36, s15, s36
	s_addc_u32 s37, s39, s37
	v_pk_mul_f32 v[30:31], v[104:105], v[60:61]
	s_waitcnt lgkmcnt(1)
	v_mfma_f32_16x16x32_bf16 v[2:5], v[10:13], v[22:25], v[2:5]
	ds_read_b128 v[10:13], v183 offset:33824
	ds_read_b128 v[18:21], v182 offset:48
	ds_read_b128 v[22:25], v183 offset:33840
	v_pk_mul_f32 v[52:53], v[104:105], v[52:53]
	v_pk_mul_f32 v[50:51], v[106:107], v[50:51]
	s_waitcnt lgkmcnt(2)
	v_mfma_f32_16x16x32_bf16 v[6:9], v[14:17], v[10:13], v[6:9]
	ds_read_b128 v[10:13], v183 offset:42272
	ds_read_b128 v[26:29], v183 offset:42288
	v_pk_mul_f32 v[48:49], v[104:105], v[48:49]
	v_pk_mul_f32 v[46:47], v[106:107], v[46:47]
	s_waitcnt lgkmcnt(1)
	v_mfma_f32_16x16x32_bf16 v[2:5], v[14:17], v[10:13], v[2:5]
	ds_read_b128 v[10:13], v182 offset:64
	v_pk_mul_f32 v[44:45], v[104:105], v[44:45]
	v_pk_mul_f32 v[42:43], v[106:107], v[42:43]
	v_mfma_f32_16x16x32_bf16 v[6:9], v[18:21], v[22:25], v[6:9]
	v_mul_f32_e64 v40, v104, v40
	v_mul_f32_e64 v41, v105, v41
	v_pk_mul_f32 v[38:39], v[106:107], v[38:39]
	s_add_i32 s14, s14, s85
	s_waitcnt lgkmcnt(1)
	v_mfma_f32_16x16x32_bf16 v[2:5], v[18:21], v[26:29], v[2:5]
	ds_read_b128 v[14:17], v183 offset:33856
	ds_read_b128 v[18:21], v182 offset:80
	ds_read_b128 v[22:25], v183 offset:33872
	s_add_i32 s13, s13, s50
	s_add_i32 s12, s12, s85
	s_waitcnt lgkmcnt(2)
	v_mfma_f32_16x16x32_bf16 v[6:9], v[10:13], v[14:17], v[6:9]
	ds_read_b128 v[14:17], v183 offset:42304
	ds_read_b128 v[26:29], v183 offset:42320
	s_add_i32 s11, s11, s51
	s_waitcnt lgkmcnt(1)
	v_mfma_f32_16x16x32_bf16 v[2:5], v[10:13], v[14:17], v[2:5]
	ds_read_b128 v[10:13], v182 offset:96
	v_mfma_f32_16x16x32_bf16 v[6:9], v[18:21], v[22:25], v[6:9]
	s_waitcnt lgkmcnt(1)
	v_mfma_f32_16x16x32_bf16 v[2:5], v[18:21], v[26:29], v[2:5]
	ds_read_b128 v[14:17], v183 offset:33888
	ds_read_b128 v[18:21], v182 offset:112
	ds_read_b128 v[22:25], v183 offset:33904
	s_waitcnt lgkmcnt(2)
	v_mfma_f32_16x16x32_bf16 v[6:9], v[10:13], v[14:17], v[6:9]
	ds_read_b128 v[14:17], v183 offset:42336
	ds_read_b128 v[26:29], v183 offset:42352
	s_waitcnt lgkmcnt(1)
	v_mfma_f32_16x16x32_bf16 v[2:5], v[10:13], v[14:17], v[2:5]
	v_mfma_f32_16x16x32_bf16 v[6:9], v[18:21], v[22:25], v[6:9]
	s_waitcnt lgkmcnt(0)
	v_mfma_f32_16x16x32_bf16 v[2:5], v[18:21], v[26:29], v[2:5]
	s_nop 5
	v_mul_f32_e32 v1, v103, v6
	v_cvt_pk_bf16_f32 v1, v1, s0
	ds_write_b16 v74, v1
	v_mul_f32_e32 v1, v198, v2
	v_cvt_pk_bf16_f32 v1, v1, s0
	ds_write_b16 v205, v1
	v_mul_f32_e32 v1, v199, v7
	v_cvt_pk_bf16_f32 v1, v1, s0
	ds_write_b16 v75, v1
	v_mul_f32_e32 v1, v200, v3
	v_cvt_pk_bf16_f32 v1, v1, s0
	ds_write_b16 v206, v1
	v_mul_f32_e32 v1, v201, v8
	v_cvt_pk_bf16_f32 v1, v1, s0
	ds_write_b16 v76, v1
	v_mul_f32_e32 v1, v202, v4
	v_cvt_pk_bf16_f32 v1, v1, s0
	ds_write_b16 v207, v1
	v_mul_f32_e32 v1, v203, v9
	v_cvt_pk_bf16_f32 v1, v1, s0
	ds_write_b16 v77, v1
	v_mul_f32_e32 v1, v204, v5
	v_cvt_pk_bf16_f32 v1, v1, s0
	ds_write_b16 v208, v1
	s_waitcnt lgkmcnt(0)
	s_barrier
	ds_read_b128 v[2:5], v184
	ds_read_b128 v[6:9], v182
	ds_read_b128 v[10:13], v182 offset:16
	ds_read_b128 v[14:17], v184 offset:16
	s_waitcnt lgkmcnt(2)
	v_mfma_f32_16x16x32_bf16 v[2:5], v[2:5], v[6:9], 0
	ds_read_b128 v[18:21], v184 offset:8448
	ds_read_b128 v[22:25], v184 offset:8464
	s_waitcnt lgkmcnt(2)
	v_mfma_f32_16x16x32_bf16 v[2:5], v[14:17], v[10:13], v[2:5]
	ds_read_b128 v[14:17], v184 offset:32
	s_waitcnt lgkmcnt(2)
	v_mfma_f32_16x16x32_bf16 v[6:9], v[18:21], v[6:9], 0
	s_waitcnt lgkmcnt(1)
	v_mfma_f32_16x16x32_bf16 v[6:9], v[22:25], v[10:13], v[6:9]
	ds_read_b128 v[10:13], v182 offset:32
	ds_read_b128 v[18:21], v182 offset:48
	ds_read_b128 v[22:25], v184 offset:48
	s_waitcnt lgkmcnt(2)
	v_mfma_f32_16x16x32_bf16 v[2:5], v[14:17], v[10:13], v[2:5]
	ds_read_b128 v[14:17], v184 offset:8480
	ds_read_b128 v[26:29], v184 offset:8496
	s_waitcnt lgkmcnt(1)
	v_mfma_f32_16x16x32_bf16 v[6:9], v[14:17], v[10:13], v[6:9]
	ds_read_b128 v[10:13], v184 offset:64
	v_mfma_f32_16x16x32_bf16 v[2:5], v[22:25], v[18:21], v[2:5]
	s_waitcnt lgkmcnt(1)
	v_mfma_f32_16x16x32_bf16 v[6:9], v[26:29], v[18:21], v[6:9]
	ds_read_b128 v[14:17], v182 offset:64
	ds_read_b128 v[18:21], v182 offset:80
	ds_read_b128 v[22:25], v184 offset:80
	s_waitcnt lgkmcnt(2)
	v_mfma_f32_16x16x32_bf16 v[2:5], v[10:13], v[14:17], v[2:5]
	ds_read_b128 v[10:13], v184 offset:8512
	ds_read_b128 v[26:29], v184 offset:8528
	s_waitcnt lgkmcnt(1)
	v_mfma_f32_16x16x32_bf16 v[6:9], v[10:13], v[14:17], v[6:9]
	ds_read_b128 v[10:13], v184 offset:96
	v_mfma_f32_16x16x32_bf16 v[2:5], v[22:25], v[18:21], v[2:5]
	s_waitcnt lgkmcnt(1)
	v_mfma_f32_16x16x32_bf16 v[6:9], v[26:29], v[18:21], v[6:9]
	ds_read_b128 v[14:17], v182 offset:96
	ds_read_b128 v[18:21], v182 offset:112
	ds_read_b128 v[22:25], v184 offset:112
	s_waitcnt lgkmcnt(2)
	v_mfma_f32_16x16x32_bf16 v[2:5], v[10:13], v[14:17], v[2:5]
	ds_read_b128 v[10:13], v184 offset:8544
	ds_read_b128 v[26:29], v184 offset:8560
	s_waitcnt lgkmcnt(1)
	v_mfma_f32_16x16x32_bf16 v[6:9], v[10:13], v[14:17], v[6:9]
	ds_read_b128 v[10:13], v185
	v_mfma_f32_16x16x32_bf16 v[2:5], v[22:25], v[18:21], v[2:5]
	s_waitcnt lgkmcnt(1)
	v_mfma_f32_16x16x32_bf16 v[6:9], v[26:29], v[18:21], v[6:9]
	ds_read_b64_tr_b16 v[18:19], v141
	ds_read_b64_tr_b16 v[20:21], v142
	ds_read_b64_tr_b16 v[14:15], v143
	ds_read_b64_tr_b16 v[16:17], v144
	s_waitcnt lgkmcnt(0)
	s_nop 5
	v_mul_f32_e64 v4, v110, v4
	v_mul_f32_e64 v5, v111, v5
	v_pk_mul_f32 v[2:3], v[108:109], v[2:3]
	v_pk_mul_f32 v[28:29], v[106:107], v[58:59]
	s_waitcnt lgkmcnt(0)
	v_mfma_f32_16x16x32_bf16 v[2:5], v[18:21], v[10:13], v[2:5]
	v_mul_f32_e64 v8, v110, v8
	v_mul_f32_e64 v9, v111, v9
	v_pk_mul_f32 v[6:7], v[108:109], v[6:7]
	s_nop 1
	v_mfma_f32_16x16x32_bf16 v[6:9], v[14:17], v[10:13], v[6:9]
	ds_read_b128 v[10:13], v185 offset:64
	ds_read_b64_tr_b16 v[18:19], v145
	ds_read_b64_tr_b16 v[20:21], v146
	ds_read_b64_tr_b16 v[14:15], v147
	ds_read_b64_tr_b16 v[16:17], v148
	s_waitcnt lgkmcnt(0)
	s_waitcnt lgkmcnt(0)
	v_mfma_f32_16x16x32_bf16 v[2:5], v[18:21], v[10:13], v[2:5]
	v_lshl_add_u64 v[18:19], s[36:37], 0, v[186:187]
	s_or_b32 s36, s38, 0xfc0
	s_mov_b32 s37, s57
	v_mfma_f32_16x16x32_bf16 v[6:9], v[14:17], v[10:13], v[6:9]
	v_lshl_add_u64 v[10:11], v[80:81], 0, s[36:37]
	v_lshl_add_u64 v[18:19], v[18:19], 0, s[56:57]
	s_nop 1
	v_cvt_pk_bf16_f32 v2, v2, v3
	v_cvt_pk_bf16_f32 v3, v4, v5
	s_cmpk_lt_i32 s14, 0x100
	s_nop 0
	v_cvt_pk_bf16_f32 v4, v6, v7
	v_lshlrev_b64 v[6:7], 13, v[10:11]
	v_lshl_add_u64 v[6:7], v[18:19], 0, v[6:7]
	v_cvt_pk_bf16_f32 v5, v8, v9
	global_store_dwordx2 v[6:7], v[2:3], off
	global_store_dwordx2 v[6:7], v[4:5], off offset:32
	v_pk_mul_f32 v[4:5], v[104:105], v[68:69]
	v_pk_mul_f32 v[2:3], v[106:107], v[66:67]
	ds_read_b64_tr_b16 v[12:13], v149
	ds_read_b64_tr_b16 v[14:15], v151
	ds_read_b64_tr_b16 v[8:9], v152
	ds_read_b64_tr_b16 v[10:11], v153
	s_waitcnt lgkmcnt(0)
	v_pk_mul_f32 v[6:7], v[104:105], v[64:65]
	ds_read_b64_tr_b16 v[20:21], v150
	ds_read_b64_tr_b16 v[22:23], v154
	ds_read_b64_tr_b16 v[16:17], v155
	ds_read_b64_tr_b16 v[18:19], v156
	s_waitcnt lgkmcnt(0)
	ds_read_b64_tr_b16 v[58:59], v157
	ds_read_b64_tr_b16 v[60:61], v158
	ds_read_b64_tr_b16 v[32:33], v159
	ds_read_b64_tr_b16 v[34:35], v160
	s_waitcnt lgkmcnt(0)
	s_nop 0
	v_mfma_f32_16x16x32_bf16 v[24:27], v[12:15], v[20:23], v[2:5]
	s_nop 2
	v_mul_f32_e64 v4, v106, v62
	v_mul_f32_e64 v5, v107, v63
	v_mfma_f32_16x16x32_bf16 v[28:31], v[12:15], v[58:61], v[28:31]
	s_nop 0
	v_mfma_f32_16x16x32_bf16 v[2:5], v[12:15], v[16:19], v[4:7]
	v_mfma_f32_16x16x32_bf16 v[12:15], v[12:15], v[32:35], v[50:53]
	s_nop 2
	v_mul_f32_e64 v52, v104, v56
	v_mul_f32_e64 v53, v105, v57
	v_pk_mul_f32 v[50:51], v[106:107], v[54:55]
	v_mfma_f32_16x16x32_bf16 v[16:19], v[8:11], v[16:19], v[46:49]
	s_nop 0
	v_mfma_f32_16x16x32_bf16 v[20:23], v[8:11], v[20:23], v[50:53]
	v_mfma_f32_16x16x32_bf16 v[42:45], v[8:11], v[58:61], v[42:45]
	v_mfma_f32_16x16x32_bf16 v[6:9], v[8:11], v[32:35], v[38:41]
	ds_read_b64_tr_b16 v[36:37], v161
	ds_read_b64_tr_b16 v[38:39], v163
	ds_read_b64_tr_b16 v[32:33], v164
	ds_read_b64_tr_b16 v[34:35], v165
	s_waitcnt lgkmcnt(0)
	ds_read_b64_tr_b16 v[50:51], v162
	ds_read_b64_tr_b16 v[52:53], v166
	ds_read_b64_tr_b16 v[46:47], v167
	ds_read_b64_tr_b16 v[48:49], v168
	s_waitcnt lgkmcnt(0)
	ds_read_b64_tr_b16 v[58:59], v169
	ds_read_b64_tr_b16 v[60:61], v170
	ds_read_b64_tr_b16 v[54:55], v171
	ds_read_b64_tr_b16 v[56:57], v172
	s_waitcnt lgkmcnt(0)
	s_nop 0
	v_mfma_f32_16x16x32_bf16 v[2:5], v[36:39], v[46:49], v[2:5]
	s_barrier
	v_mfma_f32_16x16x32_bf16 v[28:31], v[36:39], v[58:61], v[28:31]
	v_mfma_f32_16x16x32_bf16 v[10:13], v[36:39], v[54:57], v[12:15]
	s_nop 4
	v_cvt_pk_bf16_f32 v2, v2, v3
	v_cvt_pk_bf16_f32 v3, v4, v5
	ds_write_b64 v196, v[2:3] offset:8448
	v_mfma_f32_16x16x32_bf16 v[20:23], v[32:35], v[50:53], v[20:23]
	v_cvt_pk_bf16_f32 v2, v28, v29
	v_cvt_pk_bf16_f32 v3, v30, v31
	ds_write_b64 v196, v[2:3] offset:16896
	v_mfma_f32_16x16x32_bf16 v[14:17], v[32:35], v[46:49], v[16:19]
	v_cvt_pk_bf16_f32 v2, v10, v11
	v_cvt_pk_bf16_f32 v3, v12, v13
	ds_write_b64 v196, v[2:3] offset:25344
	v_mfma_f32_16x16x32_bf16 v[24:27], v[36:39], v[50:53], v[24:27]
	v_cvt_pk_bf16_f32 v2, v20, v21
	v_cvt_pk_bf16_f32 v3, v22, v23
	ds_write_b64 v197, v[2:3]
	v_mfma_f32_16x16x32_bf16 v[36:39], v[32:35], v[58:61], v[42:45]
	v_cvt_pk_bf16_f32 v2, v14, v15
	v_cvt_pk_bf16_f32 v3, v16, v17
	ds_write_b64 v197, v[2:3] offset:8448
	v_mfma_f32_16x16x32_bf16 v[6:9], v[32:35], v[54:57], v[6:9]
	v_cvt_pk_bf16_f32 v18, v24, v25
	s_nop 2
	v_cvt_pk_bf16_f32 v2, v36, v37
	v_cvt_pk_bf16_f32 v3, v38, v39
	v_cvt_pk_bf16_f32 v19, v26, v27
	ds_write_b64 v197, v[2:3] offset:16896
	v_cvt_pk_bf16_f32 v2, v6, v7
	v_cvt_pk_bf16_f32 v3, v8, v9
	ds_write_b64 v196, v[18:19]
	ds_write_b64 v197, v[2:3] offset:25344
	s_waitcnt lgkmcnt(0)
	s_barrier
	s_cbranch_scc1 .LBB0_434
